# main GEMM peeled first iteration: DMA landing wait no longer drains the previous tile's 16 epilogue stores (vmcnt(24) with a previous tile / 6 for the first), missing piece waited two sections later w
# speedup vs baseline: 1.0106x; 1.0007x over previous
; #define WAIT_V(n) asm volatile("s_waitcnt vmcnt(" #n ")" ::: "memory")
; #define BAR __builtin_amdgcn_s_barrier()
; #define STG(P, PTR, LD, O0) do { const bf16_t* _g = (PTR); \
;     __builtin_amdgcn_global_load_lds((const unsigned*)(_g + O0), (lds_u32*)((P) + swave * 1024), 16, 0, 0); \
;     __builtin_amdgcn_global_load_lds((const unsigned*)(_g + (size_t)64 * (LD) + O0), (lds_u32*)((P) + swave * 1024 + 8192), 16, 0, 0); } while (0)
; #define WAIT_V(n) asm volatile("s_waitcnt vmcnt(" #n ")" ::: "memory")
; #define BAR __builtin_amdgcn_s_barrier()
; __device__ __forceinline__ void gemm_stream(int swave, const GemmJob& J, char* shm, int vb, int G) {
;     ...
;   const int wid = tidx >> 6, lane = tidx & 63, wr = wid >> 2, wc = wid & 3, fr = lane & 15, fq = lane >> 4;
;   unsigned offA0, offA1, offB0;
;   { int _r, _c; stage_rc(tidx * 16, _r, _c); offA0 = _r * lda + _c; offA1 = _r * lda1 + _c; const int _rb = (_r & ~31) + perm32(_r & 31); offB0 = _rb * ldb + _c; }
;   const size_t hB = (size_t)128 * ldb;
;   int cg, cbrow, cbcol; const bf16_t* cA; const bf16_t* cA1; const bf16_t* cB;
;   auto decode = [&](int id, int& g, int& brow, int& bcol, const bf16_t*& pA, const bf16_t*& pA1, const bf16_t*& pB) {
;     int pm, pn; g = 0;
;     if (J.nb == 1) tile_map(id, J.nM, J.nN, pm, pn);
;     else { g = id / per; const int rem = id - g * per; pm = rem / J.nN; pn = rem - pm * J.nN; }
;     brow = pm * 256; bcol = pn * 256;
;     pA = J.A + (size_t)g * J.strideA + (size_t)brow * lda; pA1 = J.A1 + (size_t)g * J.strideA + (size_t)brow * lda1; pB = J.Bt + (size_t)g * J.strideB + (size_t)bcol * ldb;
;   };
;   int id = vb;
;   decode(id, cg, cbrow, cbcol, cA, cA1, cB);
;   f32x4 acc[2][2][4][2] = {};
;   bf16x8 At[4][2], B0[2][2], B1[2][2];
;   STG(SB(0, 0), cB, ldb, offB0); STGA(SA(0, 0), cA, cA1, 0, 0); STG(SB(0, 1), cB + hB, ldb, offB0); STGA(SA(0, 1), cA, cA1, 0, 1);
;   if (wr == 1) BAR;
;   WAIT_V(4); BAR;
;   STG(SB(1, 0), cB + 64, ldb, offB0); STGA(SA(1, 0), cA, cA1, 1, 0); STG(SB(1, 1), cB + hB + 64, ldb, offB0);
;   WAIT_V(6); BAR;
.LBB0_725:
	s_or_b64 exec, exec, s[6:7]
	v_mad_u64_u32 v[138:139], s[6:7], v17, s37, v[2:3]
	s_mul_i32 s6, s10, s37
	s_mul_hi_u32 s7, s5, s37
	s_add_i32 s7, s7, s6
	s_mul_i32 s6, s5, s37
	s_lshr_b32 s49, s76, 6
	s_lshl_b64 s[6:7], s[6:7], 1
	v_readlane_b32 s10, v247, 55
	v_readlane_b32 s11, v247, 56
	s_add_u32 s16, s10, s6
	s_addc_u32 s17, s11, s7
	s_add_u32 s50, s10, 0xc000000
	v_readlane_b32 s7, v247, 28
	s_addc_u32 s51, s11, 0
	s_add_i32 s6, s7, s89
	v_lshl_add_u64 v[4:5], v[4:5], 0, s[22:23]
	s_mov_b32 m0, s6
	s_waitcnt vmcnt(4)
	s_barrier
	global_load_lds_dwordx4 v[4:5], off
	v_lshl_add_u64 v[4:5], v[6:7], 0, s[22:23]
	s_add_i32 m0, s6, 0x2000
	s_add_i32 s54, s42, 0x8000
	global_load_lds_dwordx4 v[4:5], off
	v_lshl_add_u64 v[4:5], v[8:9], 0, s[22:23]
	s_mov_b32 m0, s54
	s_add_i32 s55, s42, 0xa000
	v_readlane_b32 s10, v247, 29
	global_load_lds_dwordx4 v[4:5], off
	v_lshl_add_u64 v[4:5], v[10:11], 0, s[22:23]
	s_mov_b32 m0, s55
	s_add_i32 s6, s10, s89
	global_load_lds_dwordx4 v[4:5], off
	v_lshl_add_u64 v[4:5], v[12:13], 0, s[22:23]
	s_mov_b32 m0, s6
	v_and_b32_e32 v1, 15, v135
	global_load_lds_dwordx4 v[4:5], off
	v_lshl_add_u64 v[4:5], v[14:15], 0, s[22:23]
	s_add_i32 m0, s6, 0x2000
	v_bfe_u32 v19, v135, 4, 2
	global_load_lds_dwordx4 v[4:5], off
	v_lshlrev_b32_e32 v4, 2, v135
	v_lshlrev_b32_e32 v6, 4, v19
	v_lshlrev_b32_e32 v2, 6, v1
	v_and_b32_e32 v7, 32, v4
	v_bitop3_b32 v8, v6, v7, v2 bitop3:0x36
	s_add_i32 s6, 0, 0x10000
	v_add_u32_e32 v9, s6, v8
	s_add_i32 s6, 0, 0x14000
	v_add_u32_e32 v10, s6, v8
	v_lshlrev_b32_e32 v14, 6, v135
	s_movk_i32 s6, 0x3c0
	v_bfe_u32 v18, v135, 6, 2
	s_waitcnt vmcnt(6)
	v_lshlrev_b32_e32 v13, 13, v16
	v_and_or_b32 v6, v14, s6, v6
	v_lshlrev_b32_e32 v5, 12, v18
	v_add_u32_e32 v11, s7, v8
	v_add_u32_e32 v12, s10, v8
	v_lshlrev_b32_e32 v2, 5, v18
	v_lshlrev_b32_e32 v4, 3, v19
	v_add_u32_e32 v8, 0, v8
	v_xad_u32 v6, v6, v7, 0
	v_or_b32_e32 v7, 0x800, v13
	v_or_b32_e32 v14, 0x1000, v13
	v_or_b32_e32 v15, 0x1800, v13
	v_lshl_or_b32 v1, v16, 6, v1
	v_add_u32_e32 v139, v9, v5
	v_add_u32_e32 v144, v8, v13
	v_add_u32_e32 v145, v6, v7
	v_add_u32_e32 v159, v6, v14
	v_add_u32_e32 v160, v6, v15
	v_add_u32_e32 v161, v10, v5
	v_add_u32_e32 v162, v11, v5
	v_add_u32_e32 v163, v12, v5
	v_lshlrev_b32_e32 v140, 1, v2
	v_lshlrev_b32_e32 v142, 1, v4
	s_mov_b64 s[10:11], s[8:9]
	s_mov_b64 s[12:13], s[16:17]
	s_mov_b64 s[14:15], s[2:3]
	s_barrier
	s_mov_b32 s75, 0

; #define LDA(dst, b, h) for (int m = 0; m < 4; ++m) for (int k = 0; k < 2; ++k) \
;     dst[m][k] = *reinterpret_cast<const bf16x8*>(SA(b, h) + lds_byte(wr * 64 + m * 16 + fr, k * 32 + fq * 8))
; #define LDB(dst, b, h) for (int n = 0; n < 2; ++n) for (int k = 0; k < 2; ++k) \
;     dst[n][k] = *reinterpret_cast<const bf16x8*>(SB(b, h) + lds_byte(wc * 32 + n * 16 + fr, k * 32 + fq * 8))
; #define MMA(ai, bj, At_, Bt_) do { __builtin_amdgcn_s_setprio(1); \
;     for (int m = 0; m < 4; ++m) for (int n = 0; n < 2; ++n) for (int k = 0; k < 2; ++k) \
;       acc[ai][bj][m][n] = __builtin_amdgcn_mfma_f32_16x16x32_bf16(Bt_[n][k], At_[m][k], acc[ai][bj][m][n], 0, 0, 0); \
;     __builtin_amdgcn_s_setprio(0); } while (0)
; #define WAIT_V(n) asm volatile("s_waitcnt vmcnt(" #n ")" ::: "memory")
; #define WAIT_L(n) asm volatile("s_waitcnt lgkmcnt(" #n ")" ::: "memory")
; #define BAR __builtin_amdgcn_s_barrier()
; #define SCHED __builtin_amdgcn_sched_barrier(0)
; #define STG(P, PTR, LD, O0) do { const bf16_t* _g = (PTR); \
;     __builtin_amdgcn_global_load_lds((const unsigned*)(_g + O0), (lds_u32*)((P) + swave * 1024), 16, 0, 0); \
;     __builtin_amdgcn_global_load_lds((const unsigned*)(_g + (size_t)64 * (LD) + O0), (lds_u32*)((P) + swave * 1024 + 8192), 16, 0, 0); } while (0)
; #define LDA(dst, b, h) for (int m = 0; m < 4; ++m) for (int k = 0; k < 2; ++k) \
;     dst[m][k] = *reinterpret_cast<const bf16x8*>(SA(b, h) + lds_byte(wr * 64 + m * 16 + fr, k * 32 + fq * 8))
; #define WAIT_V(n) asm volatile("s_waitcnt vmcnt(" #n ")" ::: "memory")
; __device__ __forceinline__ void gemm_stream(int swave, const GemmJob& J, char* shm, int vb, int G) {
;     ...
;     for (int t = 0; t < nt; t += 2) {
;       const bool last = (t == nt - 2);
;       const bf16_t* xA = last ? nA : cA; const bf16_t* xA1 = last ? nA1 : cA1; const int k2 = last ? 0 : t + 2;
;       const bf16_t* b2 = last ? nB : cB + (size_t)(t + 2) * 64; const bf16_t* b3 = b2 + 64;
;       LDB(B0, 0, 0); SCHED; LDA(At, 0, 0); STGA(SA(1, 1), cA, cA1, t + 1, 1);
;       WAIT_L(8); BAR; WAIT_L(0); MMA(0, 0, At, B0); BAR; SCHED;
;       LDB(B1, 0, 1); STG(SB(0, 0), b2, ldb, offB0);
;       BAR; WAIT_L(0); MMA(0, 1, At, B1); BAR;
;       LDA(At, 0, 1); STGA(SA(0, 0), xA, xA1, k2, 0);
;       BAR; WAIT_L(0); MMA(1, 0, At, B0); BAR; SCHED;
;       STG(SB(0, 1), b2 + hB, ldb, offB0);
;       WAIT_V(6); BAR; MMA(1, 1, At, B1); BAR;
.LBB0_728:
	s_add_u32 s20, s2, 0x100
	s_addc_u32 s21, s3, 0
	s_mov_b32 s2, 0
	s_mov_b32 s29, 2
	ds_read_b128 v[164:167], v139
	ds_read_b128 v[168:171], v139 offset:1024
	ds_read_b128 v[172:175], v139 offset:2048
	ds_read_b128 v[176:179], v139 offset:3072
	s_cmp_eq_u32 s49, s29
	s_cselect_b64 s[68:69], -1, 0
	s_and_b64 s[64:65], s[68:69], exec
	s_cselect_b32 s52, s10, s8
	s_cselect_b32 s64, s11, s9
	s_add_i32 s33, s2, 2
	s_and_b64 s[68:69], s[68:69], exec
	s_cselect_b32 s71, s15, s21
	s_cselect_b32 s70, s14, s20
	s_cselect_b32 s68, 0, s33
	s_cselect_b32 s65, s12, s16
	s_cselect_b32 s66, s13, s17
	s_or_b32 s2, s2, 1
	s_cmp_lt_u32 s2, s36
	s_cselect_b64 vcc, -1, 0
	s_and_b64 s[2:3], vcc, exec
	s_cselect_b32 s3, 0, s36
	s_cselect_b32 s2, s38, s37
	s_not_b32 s3, s3
	s_add_i32 s94, s3, s29
	s_and_b64 s[72:73], vcc, exec
	s_cselect_b32 s3, s9, s17
	s_cselect_b32 s69, s8, s16
	s_lshl_b64 s[72:73], s[94:95], 7
	s_add_u32 s69, s69, s72
	s_addc_u32 s74, s3, s73
	s_mov_b32 s3, s95
	s_lshl_b64 s[72:73], s[2:3], 8
	s_add_u32 s72, s69, s72
	v_cndmask_b32_e32 v2, v138, v0, vcc
	s_addc_u32 s73, s74, s73
	s_add_i32 m0, s42, 0xc000
	s_lshl_b64 s[2:3], s[2:3], 7
	v_lshlrev_b64 v[212:213], 1, v[2:3]
	s_add_u32 s2, s72, s2
	v_lshl_add_u64 v[214:215], s[72:73], 0, v[212:213]
	s_addc_u32 s3, s73, s3
	ds_read_b128 v[180:183], v144
	ds_read_b128 v[188:191], v145
	ds_read_b128 v[196:199], v159
	ds_read_b128 v[204:207], v160
	global_load_lds_dwordx4 v[214:215], off
	v_lshl_add_u64 v[212:213], s[2:3], 0, v[212:213]
	s_add_i32 m0, s42, 0xe000
	s_nop 0
	global_load_lds_dwordx4 v[212:213], off
	s_waitcnt lgkmcnt(4)
	s_barrier
	s_waitcnt lgkmcnt(0)
	v_mfma_f32_16x16x32_bf16 v[128:131], v[164:167], v[180:183], 0
	ds_read_b128 v[184:187], v144 offset:1024
	v_mfma_f32_16x16x32_bf16 v[124:127], v[172:175], v[180:183], 0
	ds_read_b128 v[192:195], v145 offset:1024
	v_mfma_f32_16x16x32_bf16 v[120:123], v[164:167], v[188:191], 0
	ds_read_b128 v[200:203], v159 offset:1024
	v_mfma_f32_16x16x32_bf16 v[116:119], v[172:175], v[188:191], 0
	ds_read_b128 v[208:211], v160 offset:1024
	v_mfma_f32_16x16x32_bf16 v[104:107], v[164:167], v[196:199], 0
	v_mfma_f32_16x16x32_bf16 v[100:103], v[172:175], v[196:199], 0
	v_mfma_f32_16x16x32_bf16 v[88:91], v[164:167], v[204:207], 0
	v_mfma_f32_16x16x32_bf16 v[84:87], v[172:175], v[204:207], 0
	s_waitcnt lgkmcnt(0)
	v_mfma_f32_16x16x32_bf16 v[128:131], v[168:171], v[184:187], v[128:131]
	v_mfma_f32_16x16x32_bf16 v[124:127], v[176:179], v[184:187], v[124:127]
	v_mfma_f32_16x16x32_bf16 v[120:123], v[168:171], v[192:195], v[120:123]
	v_mfma_f32_16x16x32_bf16 v[116:119], v[176:179], v[192:195], v[116:119]
	v_mfma_f32_16x16x32_bf16 v[104:107], v[168:171], v[200:203], v[104:107]
	v_mfma_f32_16x16x32_bf16 v[100:103], v[176:179], v[200:203], v[100:103]
	v_mfma_f32_16x16x32_bf16 v[88:91], v[168:171], v[208:211], v[88:91]
	v_mfma_f32_16x16x32_bf16 v[84:87], v[176:179], v[208:211], v[84:87]
	s_barrier
	s_add_u32 s2, s70, s0
	s_mov_b32 m0, s43
	v_lshl_add_u64 v[228:229], s[70:71], 0, v[136:137]
	s_addc_u32 s3, s71, s1
	ds_read_b128 v[212:215], v161
	ds_read_b128 v[216:219], v161 offset:1024
	ds_read_b128 v[220:223], v161 offset:2048
	ds_read_b128 v[224:227], v161 offset:3072
	global_load_lds_dwordx4 v[228:229], off
	v_lshl_add_u64 v[230:231], s[2:3], 0, v[136:137]
	s_mov_b32 m0, s44
	s_nop 0
	global_load_lds_dwordx4 v[230:231], off
	s_barrier
	s_waitcnt lgkmcnt(0)
	v_mfma_f32_16x16x32_bf16 v[112:115], v[212:215], v[180:183], 0
	v_mfma_f32_16x16x32_bf16 v[108:111], v[220:223], v[180:183], 0
	s_cmp_lt_u32 s68, s36
	s_cselect_b64 vcc, -1, 0
	v_mfma_f32_16x16x32_bf16 v[96:99], v[212:215], v[188:191], 0
	s_and_b64 s[70:71], vcc, exec
	s_cselect_b32 s70, s38, s37
	v_mfma_f32_16x16x32_bf16 v[92:95], v[220:223], v[188:191], 0
	s_sub_i32 s69, s68, s36
	s_min_u32 s94, s68, s69
	v_mfma_f32_16x16x32_bf16 v[80:83], v[212:215], v[196:199], 0
	s_and_b64 s[72:73], vcc, exec
	s_cselect_b32 s69, s64, s66
	v_mfma_f32_16x16x32_bf16 v[76:79], v[220:223], v[196:199], 0
	s_cselect_b32 s71, s52, s65
	s_lshl_b64 s[72:73], s[94:95], 7
	v_mfma_f32_16x16x32_bf16 v[72:75], v[212:215], v[204:207], 0
	v_cndmask_b32_e32 v2, v138, v0, vcc
	s_add_u32 s72, s71, s72
	v_mfma_f32_16x16x32_bf16 v[68:71], v[220:223], v[204:207], 0
	s_mov_b32 s71, s95
	v_mfma_f32_16x16x32_bf16 v[112:115], v[216:219], v[184:187], v[112:115]
	s_addc_u32 s73, s69, s73
	v_mfma_f32_16x16x32_bf16 v[108:111], v[224:227], v[184:187], v[108:111]
	v_lshlrev_b64 v[232:233], 1, v[2:3]
	v_mfma_f32_16x16x32_bf16 v[96:99], v[216:219], v[192:195], v[96:99]
	s_lshl_b64 s[70:71], s[70:71], 7
	v_mfma_f32_16x16x32_bf16 v[92:95], v[224:227], v[192:195], v[92:95]
	v_lshl_add_u64 v[234:235], s[72:73], 0, v[232:233]
	v_mfma_f32_16x16x32_bf16 v[80:83], v[216:219], v[200:203], v[80:83]
	s_add_u32 s72, s72, s70
	v_mfma_f32_16x16x32_bf16 v[76:79], v[224:227], v[200:203], v[76:79]
	s_mov_b32 m0, s42
	v_mfma_f32_16x16x32_bf16 v[72:75], v[216:219], v[208:211], v[72:75]
	s_addc_u32 s73, s73, s71
	v_mfma_f32_16x16x32_bf16 v[68:71], v[224:227], v[208:211], v[68:71]
	s_barrier
	ds_read_b128 v[180:183], v144 offset:16384
	ds_read_b128 v[188:191], v145 offset:16384
	ds_read_b128 v[196:199], v159 offset:16384
	ds_read_b128 v[204:207], v160 offset:16384
	global_load_lds_dwordx4 v[234:235], off
	v_lshl_add_u64 v[234:235], s[72:73], 0, v[232:233]
	s_mov_b32 m0, s39
	s_nop 0
	global_load_lds_dwordx4 v[234:235], off
	s_barrier
; #define LDA(dst, b, h) for (int m = 0; m < 4; ++m) for (int k = 0; k < 2; ++k) \
;     dst[m][k] = *reinterpret_cast<const bf16x8*>(SA(b, h) + lds_byte(wr * 64 + m * 16 + fr, k * 32 + fq * 8))
; #define LDB(dst, b, h) for (int n = 0; n < 2; ++n) for (int k = 0; k < 2; ++k) \
;     dst[n][k] = *reinterpret_cast<const bf16x8*>(SB(b, h) + lds_byte(wc * 32 + n * 16 + fr, k * 32 + fq * 8))
; #define MMA(ai, bj, At_, Bt_) do { __builtin_amdgcn_s_setprio(1); \
;     for (int m = 0; m < 4; ++m) for (int n = 0; n < 2; ++n) for (int k = 0; k < 2; ++k) \
;       acc[ai][bj][m][n] = __builtin_amdgcn_mfma_f32_16x16x32_bf16(Bt_[n][k], At_[m][k], acc[ai][bj][m][n], 0, 0, 0); \
;     __builtin_amdgcn_s_setprio(0); } while (0)
; #define WAIT_V(n) asm volatile("s_waitcnt vmcnt(" #n ")" ::: "memory")
; #define WAIT_L(n) asm volatile("s_waitcnt lgkmcnt(" #n ")" ::: "memory")
; #define BAR __builtin_amdgcn_s_barrier()
; #define SCHED __builtin_amdgcn_sched_barrier(0)
; #define STG(P, PTR, LD, O0) do { const bf16_t* _g = (PTR); \
;     __builtin_amdgcn_global_load_lds((const unsigned*)(_g + O0), (lds_u32*)((P) + swave * 1024), 16, 0, 0); \
;     __builtin_amdgcn_global_load_lds((const unsigned*)(_g + (size_t)64 * (LD) + O0), (lds_u32*)((P) + swave * 1024 + 8192), 16, 0, 0); } while (0)
; #define LDA(dst, b, h) for (int m = 0; m < 4; ++m) for (int k = 0; k < 2; ++k) \
;     dst[m][k] = *reinterpret_cast<const bf16x8*>(SA(b, h) + lds_byte(wr * 64 + m * 16 + fr, k * 32 + fq * 8))
; #define LDB(dst, b, h) for (int n = 0; n < 2; ++n) for (int k = 0; k < 2; ++k) \
;     dst[n][k] = *reinterpret_cast<const bf16x8*>(SB(b, h) + lds_byte(wc * 32 + n * 16 + fr, k * 32 + fq * 8))
; #define WAIT_V(n) asm volatile("s_waitcnt vmcnt(" #n ")" ::: "memory")
; __device__ __forceinline__ void gemm_stream(int swave, const GemmJob& J, char* shm, int vb, int G) {
;     ...
;       LDA(At, 0, 1); STGA(SA(0, 0), xA, xA1, k2, 0);
;       BAR; WAIT_L(0); MMA(1, 0, At, B0); BAR; SCHED;
;       STG(SB(0, 1), b2 + hB, ldb, offB0);
;       WAIT_V(6); BAR; MMA(1, 1, At, B1); BAR;
;       LDB(B0, 1, 0); SCHED; LDA(At, 1, 0); STGA(SA(0, 1), xA, xA1, k2, 1);
;       WAIT_L(8); BAR; WAIT_L(0); MMA(0, 0, At, B0); BAR; SCHED;
;       LDB(B1, 1, 1); STG(SB(1, 0), b3, ldb, offB0);
;       BAR; WAIT_L(0); MMA(0, 1, At, B1); BAR;
;       LDA(At, 1, 1); STGA(SA(1, 0), xA, xA1, k2 + 1, 0);
	s_waitcnt lgkmcnt(0)
	v_mfma_f32_16x16x32_bf16 v[64:67], v[164:167], v[180:183], 0
	ds_read_b128 v[184:187], v144 offset:17408
	v_mfma_f32_16x16x32_bf16 v[60:63], v[172:175], v[180:183], 0
	ds_read_b128 v[192:195], v145 offset:17408
	v_mfma_f32_16x16x32_bf16 v[56:59], v[164:167], v[188:191], 0
	ds_read_b128 v[200:203], v159 offset:17408
	v_mfma_f32_16x16x32_bf16 v[52:55], v[172:175], v[188:191], 0
	ds_read_b128 v[208:211], v160 offset:17408
	v_mfma_f32_16x16x32_bf16 v[40:43], v[164:167], v[196:199], 0
	v_mfma_f32_16x16x32_bf16 v[36:39], v[172:175], v[196:199], 0
	v_mfma_f32_16x16x32_bf16 v[24:27], v[164:167], v[204:207], 0
	v_mfma_f32_16x16x32_bf16 v[20:23], v[172:175], v[204:207], 0
	s_waitcnt lgkmcnt(0)
	v_mfma_f32_16x16x32_bf16 v[64:67], v[168:171], v[184:187], v[64:67]
	v_mfma_f32_16x16x32_bf16 v[60:63], v[176:179], v[184:187], v[60:63]
	v_mfma_f32_16x16x32_bf16 v[56:59], v[168:171], v[192:195], v[56:59]
	v_mfma_f32_16x16x32_bf16 v[52:55], v[176:179], v[192:195], v[52:55]
	v_mfma_f32_16x16x32_bf16 v[40:43], v[168:171], v[200:203], v[40:43]
	v_mfma_f32_16x16x32_bf16 v[36:39], v[176:179], v[200:203], v[36:39]
	v_mfma_f32_16x16x32_bf16 v[24:27], v[168:171], v[208:211], v[24:27]
	v_mfma_f32_16x16x32_bf16 v[20:23], v[176:179], v[208:211], v[20:23]
	s_barrier
	s_add_u32 s2, s2, s0
	s_addc_u32 s3, s3, s1
	v_lshl_add_u64 v[234:235], s[2:3], 0, v[136:137]
	s_add_u32 s2, s2, s0
	s_mov_b32 m0, s45
	s_addc_u32 s3, s3, s1
	global_load_lds_dwordx4 v[234:235], off
	v_lshl_add_u64 v[236:237], s[2:3], 0, v[136:137]
	s_mov_b32 m0, s46
	s_nop 0
	global_load_lds_dwordx4 v[236:237], off
	s_cmp_eq_u32 s75, 0
	s_cbranch_scc1 .Lgsw_first
	s_waitcnt vmcnt(24)
	s_branch .Lgsw_done
.Lgsw_first:
	s_waitcnt vmcnt(6)
.Lgsw_done:
	s_barrier
	v_mfma_f32_16x16x32_bf16 v[48:51], v[212:215], v[180:183], 0
	v_mfma_f32_16x16x32_bf16 v[44:47], v[220:223], v[180:183], 0
	v_mfma_f32_16x16x32_bf16 v[32:35], v[212:215], v[188:191], 0
	v_mfma_f32_16x16x32_bf16 v[28:31], v[220:223], v[188:191], 0
	v_mfma_f32_16x16x32_bf16 v[16:19], v[212:215], v[196:199], 0
	v_mfma_f32_16x16x32_bf16 v[12:15], v[220:223], v[196:199], 0
	v_mfma_f32_16x16x32_bf16 v[8:11], v[212:215], v[204:207], 0
	v_mfma_f32_16x16x32_bf16 v[4:7], v[220:223], v[204:207], 0
	v_mfma_f32_16x16x32_bf16 v[48:51], v[216:219], v[184:187], v[48:51]
	v_mfma_f32_16x16x32_bf16 v[44:47], v[224:227], v[184:187], v[44:47]
	v_mfma_f32_16x16x32_bf16 v[32:35], v[216:219], v[192:195], v[32:35]
	v_mfma_f32_16x16x32_bf16 v[28:31], v[224:227], v[192:195], v[28:31]
	v_mfma_f32_16x16x32_bf16 v[16:19], v[216:219], v[200:203], v[16:19]
	v_mfma_f32_16x16x32_bf16 v[12:15], v[224:227], v[200:203], v[12:15]
	v_mfma_f32_16x16x32_bf16 v[8:11], v[216:219], v[208:211], v[8:11]
	v_mfma_f32_16x16x32_bf16 v[4:7], v[224:227], v[208:211], v[4:7]
	s_barrier
	ds_read_b128 v[164:167], v162
	ds_read_b128 v[168:171], v162 offset:1024
	ds_read_b128 v[172:175], v162 offset:2048
	ds_read_b128 v[176:179], v162 offset:3072
	s_add_u32 s2, s72, s70
	s_addc_u32 s3, s73, s71
	v_lshl_add_u64 v[212:213], s[2:3], 0, v[232:233]
	s_add_u32 s2, s2, s70
	s_mov_b32 m0, s47
	s_addc_u32 s3, s3, s71
	ds_read_b128 v[180:183], v144 offset:32768
	ds_read_b128 v[188:191], v145 offset:32768
	ds_read_b128 v[196:199], v159 offset:32768
	ds_read_b128 v[204:207], v160 offset:32768
	global_load_lds_dwordx4 v[212:213], off
	v_lshl_add_u64 v[212:213], s[2:3], 0, v[232:233]
	s_mov_b32 m0, s48
	s_nop 0
	global_load_lds_dwordx4 v[212:213], off
	s_waitcnt lgkmcnt(4)
	s_barrier
	s_waitcnt lgkmcnt(0)
	v_mfma_f32_16x16x32_bf16 v[128:131], v[164:167], v[180:183], v[128:131]
	ds_read_b128 v[184:187], v144 offset:33792
	v_mfma_f32_16x16x32_bf16 v[124:127], v[172:175], v[180:183], v[124:127]
	ds_read_b128 v[192:195], v145 offset:33792
	v_mfma_f32_16x16x32_bf16 v[120:123], v[164:167], v[188:191], v[120:123]
	ds_read_b128 v[200:203], v159 offset:33792
	v_mfma_f32_16x16x32_bf16 v[116:119], v[172:175], v[188:191], v[116:119]
	ds_read_b128 v[208:211], v160 offset:33792
	v_mfma_f32_16x16x32_bf16 v[104:107], v[164:167], v[196:199], v[104:107]
	v_mfma_f32_16x16x32_bf16 v[100:103], v[172:175], v[196:199], v[100:103]
	v_mfma_f32_16x16x32_bf16 v[88:91], v[164:167], v[204:207], v[88:91]
	v_mfma_f32_16x16x32_bf16 v[84:87], v[172:175], v[204:207], v[84:87]
	s_waitcnt lgkmcnt(0)
	v_mfma_f32_16x16x32_bf16 v[128:131], v[168:171], v[184:187], v[128:131]
	v_mfma_f32_16x16x32_bf16 v[124:127], v[176:179], v[184:187], v[124:127]
	v_mfma_f32_16x16x32_bf16 v[120:123], v[168:171], v[192:195], v[120:123]
	v_mfma_f32_16x16x32_bf16 v[116:119], v[176:179], v[192:195], v[116:119]
	v_mfma_f32_16x16x32_bf16 v[104:107], v[168:171], v[200:203], v[104:107]
	v_mfma_f32_16x16x32_bf16 v[100:103], v[176:179], v[200:203], v[100:103]
	v_mfma_f32_16x16x32_bf16 v[88:91], v[168:171], v[208:211], v[88:91]
	v_mfma_f32_16x16x32_bf16 v[84:87], v[176:179], v[208:211], v[84:87]
	s_barrier
	v_lshl_add_u64 v[228:229], v[228:229], 0, s[22:23]
	s_add_i32 m0, s42, 0x18000
	ds_read_b128 v[212:215], v163
	ds_read_b128 v[216:219], v163 offset:1024
	ds_read_b128 v[220:223], v163 offset:2048
	ds_read_b128 v[224:227], v163 offset:3072
	global_load_lds_dwordx4 v[228:229], off
	v_lshl_add_u64 v[228:229], v[230:231], 0, s[22:23]
	s_add_i32 m0, s42, 0x1a000
	s_nop 0
	global_load_lds_dwordx4 v[228:229], off
	s_waitcnt vmcnt(10)
	s_barrier
; #define LDA(dst, b, h) for (int m = 0; m < 4; ++m) for (int k = 0; k < 2; ++k) \
;     dst[m][k] = *reinterpret_cast<const bf16x8*>(SA(b, h) + lds_byte(wr * 64 + m * 16 + fr, k * 32 + fq * 8))
; #define MMA(ai, bj, At_, Bt_) do { __builtin_amdgcn_s_setprio(1); \
;     for (int m = 0; m < 4; ++m) for (int n = 0; n < 2; ++n) for (int k = 0; k < 2; ++k) \
;       acc[ai][bj][m][n] = __builtin_amdgcn_mfma_f32_16x16x32_bf16(Bt_[n][k], At_[m][k], acc[ai][bj][m][n], 0, 0, 0); \
;     __builtin_amdgcn_s_setprio(0); } while (0)
; #define WAIT_V(n) asm volatile("s_waitcnt vmcnt(" #n ")" ::: "memory")
; #define WAIT_L(n) asm volatile("s_waitcnt lgkmcnt(" #n ")" ::: "memory")
; #define BAR __builtin_amdgcn_s_barrier()
; #define SCHED __builtin_amdgcn_sched_barrier(0)
; #define STG(P, PTR, LD, O0) do { const bf16_t* _g = (PTR); \
;     __builtin_amdgcn_global_load_lds((const unsigned*)(_g + O0), (lds_u32*)((P) + swave * 1024), 16, 0, 0); \
;     __builtin_amdgcn_global_load_lds((const unsigned*)(_g + (size_t)64 * (LD) + O0), (lds_u32*)((P) + swave * 1024 + 8192), 16, 0, 0); } while (0)
; #define LDA(dst, b, h) for (int m = 0; m < 4; ++m) for (int k = 0; k < 2; ++k) \
;     dst[m][k] = *reinterpret_cast<const bf16x8*>(SA(b, h) + lds_byte(wr * 64 + m * 16 + fr, k * 32 + fq * 8))
; #define MMA(ai, bj, At_, Bt_) do { __builtin_amdgcn_s_setprio(1); \
;     for (int m = 0; m < 4; ++m) for (int n = 0; n < 2; ++n) for (int k = 0; k < 2; ++k) \
;       acc[ai][bj][m][n] = __builtin_amdgcn_mfma_f32_16x16x32_bf16(Bt_[n][k], At_[m][k], acc[ai][bj][m][n], 0, 0, 0); \
;     __builtin_amdgcn_s_setprio(0); } while (0)
; #define WAIT_V(n) asm volatile("s_waitcnt vmcnt(" #n ")" ::: "memory")
; #define WAIT_L(n) asm volatile("s_waitcnt lgkmcnt(" #n ")" ::: "memory")
; #define BAR __builtin_amdgcn_s_barrier()
; #define SCHED __builtin_amdgcn_sched_barrier(0)
; __device__ __forceinline__ void gemm_stream(int swave, const GemmJob& J, char* shm, int vb, int G) {
;     ...
;       BAR; WAIT_L(0); MMA(0, 1, At, B1); BAR;
;       LDA(At, 1, 1); STGA(SA(1, 0), xA, xA1, k2 + 1, 0);
;       BAR; WAIT_L(0); MMA(1, 0, At, B0); BAR; SCHED;
;       STG(SB(1, 1), b3 + hB, ldb, offB0);
;       WAIT_V(6); BAR; MMA(1, 1, At, B1); BAR;
;     }
	s_waitcnt lgkmcnt(0)
	v_mfma_f32_16x16x32_bf16 v[112:115], v[212:215], v[180:183], v[112:115]
	v_mfma_f32_16x16x32_bf16 v[108:111], v[220:223], v[180:183], v[108:111]
	s_or_b32 s68, s68, 1
	s_cmp_lt_u32 s68, s36
	v_mfma_f32_16x16x32_bf16 v[96:99], v[212:215], v[188:191], v[96:99]
	s_cselect_b64 vcc, -1, 0
	s_and_b64 s[2:3], vcc, exec
	v_mfma_f32_16x16x32_bf16 v[92:95], v[220:223], v[188:191], v[92:95]
	s_cselect_b32 s69, s38, s37
	s_sub_i32 s2, s68, s36
	v_mfma_f32_16x16x32_bf16 v[80:83], v[212:215], v[196:199], v[80:83]
	s_min_u32 s94, s68, s2
	s_and_b64 s[2:3], vcc, exec
	v_mfma_f32_16x16x32_bf16 v[76:79], v[220:223], v[196:199], v[76:79]
	s_cselect_b32 s64, s64, s66
	s_cselect_b32 s52, s52, s65
	v_mfma_f32_16x16x32_bf16 v[72:75], v[212:215], v[204:207], v[72:75]
	s_lshl_b64 s[2:3], s[94:95], 7
	v_cndmask_b32_e32 v2, v138, v0, vcc
	v_mfma_f32_16x16x32_bf16 v[68:71], v[220:223], v[204:207], v[68:71]
	s_add_u32 s2, s52, s2
	v_mfma_f32_16x16x32_bf16 v[112:115], v[216:219], v[184:187], v[112:115]
	s_addc_u32 s3, s64, s3
	v_mfma_f32_16x16x32_bf16 v[108:111], v[224:227], v[184:187], v[108:111]
	v_lshlrev_b64 v[228:229], 1, v[2:3]
	v_mfma_f32_16x16x32_bf16 v[96:99], v[216:219], v[192:195], v[96:99]
	s_lshl_b32 s52, s69, 7
	v_mfma_f32_16x16x32_bf16 v[92:95], v[224:227], v[192:195], v[92:95]
	v_lshl_add_u64 v[230:231], s[2:3], 0, v[228:229]
	v_mfma_f32_16x16x32_bf16 v[80:83], v[216:219], v[200:203], v[80:83]
	s_add_u32 s2, s2, s52
	v_mfma_f32_16x16x32_bf16 v[76:79], v[224:227], v[200:203], v[76:79]
	s_mov_b32 m0, s54
	v_mfma_f32_16x16x32_bf16 v[72:75], v[216:219], v[208:211], v[72:75]
	s_addc_u32 s3, s3, 0
	v_mfma_f32_16x16x32_bf16 v[68:71], v[224:227], v[208:211], v[68:71]
	s_barrier
	ds_read_b128 v[180:183], v144 offset:49152
	ds_read_b128 v[188:191], v145 offset:49152
	ds_read_b128 v[196:199], v159 offset:49152
	ds_read_b128 v[204:207], v160 offset:49152
	global_load_lds_dwordx4 v[230:231], off
	v_lshl_add_u64 v[228:229], s[2:3], 0, v[228:229]
	s_mov_b32 m0, s55
	s_nop 0
	global_load_lds_dwordx4 v[228:229], off
	s_barrier
	s_waitcnt lgkmcnt(0)
	v_mfma_f32_16x16x32_bf16 v[64:67], v[164:167], v[180:183], v[64:67]
	ds_read_b128 v[184:187], v144 offset:50176
	v_mfma_f32_16x16x32_bf16 v[60:63], v[172:175], v[180:183], v[60:63]
	ds_read_b128 v[192:195], v145 offset:50176
	v_mfma_f32_16x16x32_bf16 v[56:59], v[164:167], v[188:191], v[56:59]
	ds_read_b128 v[200:203], v159 offset:50176
	v_mfma_f32_16x16x32_bf16 v[52:55], v[172:175], v[188:191], v[52:55]
	ds_read_b128 v[208:211], v160 offset:50176
	v_mfma_f32_16x16x32_bf16 v[40:43], v[164:167], v[196:199], v[40:43]
	v_mfma_f32_16x16x32_bf16 v[36:39], v[172:175], v[196:199], v[36:39]
	v_mfma_f32_16x16x32_bf16 v[24:27], v[164:167], v[204:207], v[24:27]
	v_mfma_f32_16x16x32_bf16 v[20:23], v[172:175], v[204:207], v[20:23]
	s_waitcnt lgkmcnt(0)
	v_mfma_f32_16x16x32_bf16 v[64:67], v[168:171], v[184:187], v[64:67]
	v_mfma_f32_16x16x32_bf16 v[60:63], v[176:179], v[184:187], v[60:63]
	v_mfma_f32_16x16x32_bf16 v[56:59], v[168:171], v[192:195], v[56:59]
	v_mfma_f32_16x16x32_bf16 v[52:55], v[176:179], v[192:195], v[52:55]
	v_mfma_f32_16x16x32_bf16 v[40:43], v[168:171], v[200:203], v[40:43]
	v_mfma_f32_16x16x32_bf16 v[36:39], v[176:179], v[200:203], v[36:39]
	v_mfma_f32_16x16x32_bf16 v[24:27], v[168:171], v[208:211], v[24:27]
	v_mfma_f32_16x16x32_bf16 v[20:23], v[176:179], v[208:211], v[20:23]
	s_barrier
	v_lshl_add_u64 v[164:165], v[234:235], 0, s[22:23]
	s_add_i32 m0, s42, 0x1c000
	s_nop 0
	global_load_lds_dwordx4 v[164:165], off
	v_lshl_add_u64 v[164:165], v[236:237], 0, s[22:23]
	s_add_i32 m0, s42, 0x1e000
	s_nop 0
	global_load_lds_dwordx4 v[164:165], off
	s_waitcnt vmcnt(6)
	s_barrier
	v_mfma_f32_16x16x32_bf16 v[48:51], v[212:215], v[180:183], v[48:51]
	v_mfma_f32_16x16x32_bf16 v[44:47], v[220:223], v[180:183], v[44:47]
	s_add_i32 s29, s29, 2
	v_mfma_f32_16x16x32_bf16 v[32:35], v[212:215], v[188:191], v[32:35]
	s_add_u32 s20, s20, 0x100
	v_mfma_f32_16x16x32_bf16 v[28:31], v[220:223], v[188:191], v[28:31]
	s_addc_u32 s21, s21, 0
	v_mfma_f32_16x16x32_bf16 v[16:19], v[212:215], v[196:199], v[16:19]
	s_cmp_ge_u32 s33, s49
	v_mfma_f32_16x16x32_bf16 v[12:15], v[220:223], v[196:199], v[12:15]
	s_mov_b32 s2, s33
	v_mfma_f32_16x16x32_bf16 v[8:11], v[212:215], v[204:207], v[8:11]
	v_mfma_f32_16x16x32_bf16 v[4:7], v[220:223], v[204:207], v[4:7]
	v_mfma_f32_16x16x32_bf16 v[48:51], v[216:219], v[184:187], v[48:51]
	v_mfma_f32_16x16x32_bf16 v[44:47], v[224:227], v[184:187], v[44:47]
	v_mfma_f32_16x16x32_bf16 v[32:35], v[216:219], v[192:195], v[32:35]
	v_mfma_f32_16x16x32_bf16 v[28:31], v[224:227], v[192:195], v[28:31]
	v_mfma_f32_16x16x32_bf16 v[16:19], v[216:219], v[200:203], v[16:19]
	v_mfma_f32_16x16x32_bf16 v[12:15], v[224:227], v[200:203], v[12:15]
	v_mfma_f32_16x16x32_bf16 v[8:11], v[216:219], v[208:211], v[8:11]
	v_mfma_f32_16x16x32_bf16 v[4:7], v[224:227], v[208:211], v[4:7]
	s_barrier
	s_cbranch_scc0 .LBB0_729
	s_branch .Lgemm_epi

; __device__ __forceinline__ unsigned pk2(float lo, float hi) { f32x2_t v = {lo, hi}; bf16x2_t b = __builtin_convertvector(v, bf16x2_t); return __builtin_bit_cast(unsigned, b); }
; __device__ __forceinline__ void gemm_stream(int swave, const GemmJob& J, char* shm, int vb, int G) {
;     ...
;     {
;       bf16_t* C = (bf16_t*)((char*)J.c0 + (size_t)cg * J.strideC);
; #pragma unroll
;       for (int ai = 0; ai < 2; ++ai)
; #pragma unroll
;         for (int m = 0; m < 4; ++m)
; #pragma unroll
;           for (int bj = 0; bj < 2; ++bj) {
;             const f32x4 v0 = acc[ai][bj][m][0], v1 = acc[ai][bj][m][1];
;             uint4 o; o.x = pk2(v0[0], v0[1]); o.y = pk2(v0[2], v0[3]); o.z = pk2(v1[0], v1[1]); o.w = pk2(v1[2], v1[3]);
;             *(uint4*)(C + (size_t)(cbrow + ai * 128 + wr * 64 + m * 16 + fr) * J.ldc + cbcol + bj * 128 + wc * 32 + fq * 8) = o;
;           }
;     }
;     if (!has_next) break;
; #pragma unroll
;     for (int a_ = 0; a_ < 2; ++a_)
; #pragma unroll
;       for (int b_ = 0; b_ < 2; ++b_)
; #pragma unroll
;         for (int m = 0; m < 4; ++m)
; #pragma unroll
;           for (int n = 0; n < 2; ++n) acc[a_][b_][m][n] = (f32x4){0.f, 0.f, 0.f, 0.f};
;     id = nid; cg = ng; cbrow = nbrow; cbcol = nbcol; cA = nA; cA1 = nA1; cB = nB;
;   }
.Lgemm_epi:
	s_mov_b32 s75, 1
	v_add_u32_e32 v164, s5, v1
	s_ashr_i32 s5, s4, 31
	s_lshl_b64 s[2:3], s[4:5], 1
	v_ashrrev_i32_e32 v2, 31, v164
	s_add_u32 s2, s50, s2
	v_cvt_pk_bf16_f32 v128, v128, v129
	v_cvt_pk_bf16_f32 v129, v130, v131
	v_cvt_pk_bf16_f32 v130, v124, v125
	v_mul_lo_u32 v2, v2, s18
	v_mad_u64_u32 v[124:125], s[4:5], v164, s18, 0
	s_addc_u32 s3, s51, s3
	v_add_u32_e32 v125, v125, v2
	v_lshl_add_u64 v[124:125], v[124:125], 1, s[2:3]
	v_mov_b32_e32 v141, v3
	v_lshl_add_u64 v[124:125], v[124:125], 0, v[140:141]
	v_mov_b32_e32 v143, v3
	v_lshl_add_u64 v[124:125], v[124:125], 0, v[142:143]
	s_lshl_b32 s2, s18, 5
	s_mov_b32 s3, 0
	s_mul_i32 s4, s18, 0xa0
	s_mov_b32 s5, 0
	v_cvt_pk_bf16_f32 v112, v112, v113
	v_cvt_pk_bf16_f32 v113, v114, v115
	v_cvt_pk_bf16_f32 v114, v108, v109
	v_cvt_pk_bf16_f32 v115, v110, v111
	global_store_dwordx4 v[124:125], v[112:115], off offset:256
	v_cvt_pk_bf16_f32 v131, v126, v127
	v_cvt_pk_bf16_f32 v96, v96, v97
	v_lshl_add_u64 v[112:113], v[124:125], 0, s[2:3]
	v_cvt_pk_bf16_f32 v97, v98, v99
	v_cvt_pk_bf16_f32 v98, v92, v93
	v_cvt_pk_bf16_f32 v99, v94, v95
	global_store_dwordx4 v[124:125], v[128:131], off
	global_store_dwordx4 v[112:113], v[96:99], off offset:256
	v_cvt_pk_bf16_f32 v108, v120, v121
	v_cvt_pk_bf16_f32 v109, v122, v123
	v_lshl_add_u64 v[96:97], v[112:113], 0, s[2:3]
	v_cvt_pk_bf16_f32 v110, v116, v117
	v_cvt_pk_bf16_f32 v111, v118, v119
	v_cvt_pk_bf16_f32 v80, v80, v81
	v_cvt_pk_bf16_f32 v81, v82, v83
	v_cvt_pk_bf16_f32 v82, v76, v77
	v_cvt_pk_bf16_f32 v83, v78, v79
	global_store_dwordx4 v[112:113], v[108:111], off
	global_store_dwordx4 v[96:97], v[80:83], off offset:256
	v_cvt_pk_bf16_f32 v64, v64, v65
	v_cvt_pk_bf16_f32 v65, v66, v67
	v_lshl_add_u64 v[80:81], v[96:97], 0, s[2:3]
	v_cvt_pk_bf16_f32 v66, v60, v61
	v_lshl_add_u64 v[60:61], v[80:81], 0, s[4:5]
	v_cvt_pk_bf16_f32 v72, v72, v73
	v_cvt_pk_bf16_f32 v73, v74, v75
	v_cvt_pk_bf16_f32 v74, v68, v69
	v_cvt_pk_bf16_f32 v67, v62, v63
	v_cvt_pk_bf16_f32 v92, v104, v105
	v_cvt_pk_bf16_f32 v93, v106, v107
	v_cvt_pk_bf16_f32 v94, v100, v101
	v_cvt_pk_bf16_f32 v95, v102, v103
	v_cvt_pk_bf16_f32 v76, v88, v89
	v_cvt_pk_bf16_f32 v77, v90, v91
	v_cvt_pk_bf16_f32 v78, v84, v85
	v_cvt_pk_bf16_f32 v79, v86, v87
	v_cvt_pk_bf16_f32 v75, v70, v71
	v_cvt_pk_bf16_f32 v48, v48, v49
	v_cvt_pk_bf16_f32 v49, v50, v51
	v_cvt_pk_bf16_f32 v50, v44, v45
	v_cvt_pk_bf16_f32 v51, v46, v47
	global_store_dwordx4 v[96:97], v[92:95], off
	global_store_dwordx4 v[80:81], v[76:79], off
	global_store_dwordx4 v[80:81], v[72:75], off offset:256
	global_store_dwordx4 v[60:61], v[48:51], off offset:256
	v_cvt_pk_bf16_f32 v32, v32, v33
	v_cvt_pk_bf16_f32 v33, v34, v35
	v_lshl_add_u64 v[48:49], v[60:61], 0, s[2:3]
	v_cvt_pk_bf16_f32 v34, v28, v29
	v_cvt_pk_bf16_f32 v35, v30, v31
	global_store_dwordx4 v[60:61], v[64:67], off
	global_store_dwordx4 v[48:49], v[32:35], off offset:256
	v_cvt_pk_bf16_f32 v44, v56, v57
	v_cvt_pk_bf16_f32 v45, v58, v59
	v_lshl_add_u64 v[32:33], v[48:49], 0, s[2:3]
	v_cvt_pk_bf16_f32 v46, v52, v53
	v_cvt_pk_bf16_f32 v47, v54, v55
	v_cvt_pk_bf16_f32 v16, v16, v17
	v_cvt_pk_bf16_f32 v17, v18, v19
	v_cvt_pk_bf16_f32 v18, v12, v13
	v_cvt_pk_bf16_f32 v19, v14, v15
	global_store_dwordx4 v[48:49], v[44:47], off
	global_store_dwordx4 v[32:33], v[16:19], off offset:256
	v_cvt_pk_bf16_f32 v28, v40, v41
	v_cvt_pk_bf16_f32 v29, v42, v43
	v_lshl_add_u64 v[16:17], v[32:33], 0, s[2:3]
	v_cvt_pk_bf16_f32 v30, v36, v37
	v_cvt_pk_bf16_f32 v31, v38, v39
	v_cvt_pk_bf16_f32 v12, v24, v25
	v_cvt_pk_bf16_f32 v13, v26, v27
	v_cvt_pk_bf16_f32 v14, v20, v21
	v_cvt_pk_bf16_f32 v15, v22, v23
	v_cvt_pk_bf16_f32 v8, v8, v9
	v_cvt_pk_bf16_f32 v9, v10, v11
	v_cvt_pk_bf16_f32 v10, v4, v5
	v_cvt_pk_bf16_f32 v11, v6, v7
	s_and_b64 vcc, exec, s[6:7]
	s_mov_b64 s[2:3], s[14:15]
	s_mov_b64 s[16:17], s[12:13]
	s_mov_b64 s[8:9], s[10:11]
	s_mov_b32 s4, s56
	s_mov_b32 s5, s28
	global_store_dwordx4 v[32:33], v[28:31], off
	global_store_dwordx4 v[16:17], v[12:15], off
	global_store_dwordx4 v[16:17], v[8:11], off offset:256
	s_cbranch_vccz .LBB0_726
	s_waitcnt vmcnt(0)
	s_movk_i32 s66, 0x100
	v_cmp_gt_u32_e32 vcc, s66, v135
	s_and_saveexec_b64 s[0:1], vcc
	s_cbranch_execz .LBB0_733
	s_barrier
